# hand-scheduled software-pipelined diff-attention pass: 3-slot LDS ring, QK/softmax/PV overlapped across tiles
# speedup vs baseline: 1.0370x; 1.0370x over previous
; __device__ __forceinline__ float bf2f(unsigned short b) { return __uint_as_float((unsigned)b << 16); }
; template <int DV>
; __device__ __forceinline__ void attn_pass(const int tid, unsigned char* smem, const bf16_t* Q0, int qpitch, const bf16_t* Kb, int kpitch, const bf16_t* Vb, int vpitch,
;                                           int b, int ntiles, float kmax, f32x16 (&o)[DV / 32], float& linv) {
;     ...
;     const int lane = tid & 63, wid = __builtin_amdgcn_readfirstlane(tid >> 6), r32 = lane & 31, hi = lane >> 5;
;     bf16x8 qf[4];
;     { const bf16_t* qp = Q0 + (size_t)(wid * 32 + r32) * qpitch + 8 * hi;
; #pragma unroll
;       for (int ds = 0; ds < 4; ++ds) qf[ds] = *(const bf16x8*)(qp + 16 * ds); }
;     float ssq = 0.f;
; #pragma unroll
;     for (int ds = 0; ds < 4; ++ds)
; #pragma unroll
;         for (int j = 0; j < 8; ++j) { const float f = bf2f((unsigned short)qf[ds][j]); ssq += f * f; }
;     ssq = sum_x32(ssq);
;     const float nshift = -sqrtf(ssq) * kmax;
; #pragma unroll
;     for (int d0 = 0; d0 < DV / 32; ++d0)
; #pragma unroll
;         for (int r = 0; r < 16; ++r) o[d0][r] = 0.f;
;     float lsum = 0.f;
;     const int krow = tid >> 3, kch = tid & 7;
;     u32x4 kreg, vreg[NV];
;     auto tile_row = [&](int kt) -> size_t { return kt < 4 ? (size_t)(NLAT + 256 * b + 64 * kt) : (size_t)(SEQ * b + 64 * (kt - 4)); };
;     auto gload = [&](int kt) {
;         const size_t rb = tile_row(kt);
;         kreg = *(const u32x4*)(Kb + (rb + krow) * kpitch + 8 * kch);
; #pragma unroll
;         for (int i = 0; i < NV; ++i) { const int item = tid + 512 * i; const int vr = (DV == 64) ? (item >> 3) : (item >> 4), vc = (DV == 64) ? (item & 7) : (item & 15);
;             vreg[i] = *(const u32x4*)(Vb + (rb + vr) * vpitch + 8 * vc); }
;     };
;     auto lwrite = [&](int buf) {
;         unsigned char* Ks = smem + buf * BUF; unsigned char* Vs = Ks + KBYTES;
;         *(u32x4*)(Ks + krow * KP + 16 * kch) = kreg;
; #pragma unroll
;         for (int i = 0; i < NV; ++i) { const int item = tid + 512 * i; const int vr = (DV == 64) ? (item >> 3) : (item >> 4), vc = (DV == 64) ? (item & 7) : (item & 15);
;             *(u32x4*)(Vs + vr * VP + 16 * vc) = vreg[i]; }
;     };
;     gload(0); lwrite(0); __syncthreads();
.LBB0_405:
	s_xor_b64 s[14:15], s[16:17], -1
	s_lshl_b64 s[0:1], s[0:1], 1
	s_add_u32 s2, s28, s0
	s_addc_u32 s3, s29, s1
	s_add_u32 s16, s30, s0
	v_readfirstlane_b32 s0, v197
	s_addc_u32 s17, s31, s1
	s_ashr_i32 s0, s0, 1
	s_andn2_b32 s0, s0, 31
	v_or_b32_e32 v0, s0, v218
	v_ashrrev_i32_e32 v1, 31, v0
	v_lshlrev_b64 v[0:1], 11, v[0:1]
	v_lshl_add_u64 v[0:1], s[2:3], 0, v[0:1]
	v_lshl_add_u64 v[0:1], v[0:1], 0, v[192:193]
	global_load_dwordx4 v[96:99], v[0:1], off
	global_load_dwordx4 v[100:103], v[0:1], off offset:32
	global_load_dwordx4 v[104:107], v[0:1], off offset:64
	global_load_dwordx4 v[108:111], v[0:1], off offset:96
	s_mov_b32 s0, 0xf800000
	v_mov_b32_e32 v169, v193
	v_lshl_add_u64 v[170:171], s[16:17], 0, v[168:169]
	v_mov_b32_e32 v63, v193
	s_waitcnt vmcnt(3)
	v_and_b32_e32 v1, 0xffff0000, v96
	v_lshlrev_b32_e32 v0, 16, v96
	v_mul_f32_e32 v2, v1, v1
	v_fmac_f32_e32 v2, v0, v0
	v_lshlrev_b32_e32 v0, 16, v97
	v_fmac_f32_e32 v2, v0, v0
	v_and_b32_e32 v0, 0xffff0000, v97
	v_fmac_f32_e32 v2, v0, v0
	v_lshlrev_b32_e32 v0, 16, v98
	v_fmac_f32_e32 v2, v0, v0
	v_and_b32_e32 v0, 0xffff0000, v98
	v_fmac_f32_e32 v2, v0, v0
	v_lshlrev_b32_e32 v0, 16, v99
	v_fmac_f32_e32 v2, v0, v0
	v_and_b32_e32 v0, 0xffff0000, v99
	v_fmac_f32_e32 v2, v0, v0
	s_waitcnt vmcnt(2)
	v_lshlrev_b32_e32 v0, 16, v100
	v_fmac_f32_e32 v2, v0, v0
	v_and_b32_e32 v0, 0xffff0000, v100
	v_fmac_f32_e32 v2, v0, v0
	v_lshlrev_b32_e32 v0, 16, v101
	v_fmac_f32_e32 v2, v0, v0
	v_and_b32_e32 v0, 0xffff0000, v101
	v_fmac_f32_e32 v2, v0, v0
	v_lshlrev_b32_e32 v0, 16, v102
	v_fmac_f32_e32 v2, v0, v0
	v_and_b32_e32 v0, 0xffff0000, v102
	v_fmac_f32_e32 v2, v0, v0
	v_lshlrev_b32_e32 v0, 16, v103
	v_fmac_f32_e32 v2, v0, v0
	v_and_b32_e32 v0, 0xffff0000, v103
	v_fmac_f32_e32 v2, v0, v0
	s_waitcnt vmcnt(1)
	v_lshlrev_b32_e32 v0, 16, v104
	v_fmac_f32_e32 v2, v0, v0
	v_and_b32_e32 v0, 0xffff0000, v104
	v_fmac_f32_e32 v2, v0, v0
	v_lshlrev_b32_e32 v0, 16, v105
	v_fmac_f32_e32 v2, v0, v0
	v_and_b32_e32 v0, 0xffff0000, v105
	v_fmac_f32_e32 v2, v0, v0
	v_lshlrev_b32_e32 v0, 16, v106
	v_fmac_f32_e32 v2, v0, v0
	v_and_b32_e32 v0, 0xffff0000, v106
	v_fmac_f32_e32 v2, v0, v0
	v_lshlrev_b32_e32 v0, 16, v107
	v_fmac_f32_e32 v2, v0, v0
	v_and_b32_e32 v0, 0xffff0000, v107
	v_fmac_f32_e32 v2, v0, v0
	s_waitcnt vmcnt(0)
	v_lshlrev_b32_e32 v0, 16, v108
	v_fmac_f32_e32 v2, v0, v0
	v_and_b32_e32 v0, 0xffff0000, v108
	v_fmac_f32_e32 v2, v0, v0
	v_lshlrev_b32_e32 v0, 16, v109
	v_fmac_f32_e32 v2, v0, v0
	v_and_b32_e32 v0, 0xffff0000, v109
	v_fmac_f32_e32 v2, v0, v0
	v_and_b32_e32 v1, 0xffff0000, v110
	v_lshlrev_b32_e32 v0, 16, v110
	v_pk_mul_f32 v[0:1], v[0:1], v[0:1]
	s_nop 0
	v_add_f32_e32 v0, v0, v2
	v_add_f32_e32 v2, v1, v0
	v_and_b32_e32 v1, 0xffff0000, v111
	v_lshlrev_b32_e32 v0, 16, v111
	v_pk_mul_f32 v[0:1], v[0:1], v[0:1]
	s_nop 0
	v_add_f32_e32 v0, v0, v2
	v_add_f32_e32 v0, v1, v0
	v_mov_b32_e32 v1, v0
	s_nop 1
	v_permlane32_swap_b32_e32 v0, v1
	v_add_f32_e32 v0, v0, v1
	v_cmp_gt_f32_e32 vcc, s0, v0
	v_mul_f32_e32 v1, 0x4f800000, v0
	s_nop 0
	v_cndmask_b32_e32 v0, v0, v1, vcc
	v_sqrt_f32_e32 v1, v0
	s_nop 0
	v_add_u32_e32 v2, -1, v1
	v_fma_f32 v3, -v2, v1, v0
	v_cmp_ge_f32_e64 s[0:1], 0, v3
	v_add_u32_e32 v3, 1, v1
	s_nop 0
	v_cndmask_b32_e64 v2, v1, v2, s[0:1]
	v_fma_f32 v1, -v3, v1, v0
	v_cmp_lt_f32_e64 s[0:1], 0, v1
	s_nop 1
	v_cndmask_b32_e64 v1, v2, v3, s[0:1]
	v_mul_f32_e32 v2, 0x37800000, v1
	v_cndmask_b32_e32 v1, v1, v2, vcc
	v_cmp_class_f32_e32 vcc, v0, v227
	s_nop 1
	v_cndmask_b32_e32 v0, v1, v0, vcc
	v_mul_f32_e64 v32, v214, -v0
	v_mov_b32_e32 v33, v32
	v_mov_b32_e32 v34, v32
	v_mov_b32_e32 v35, v32
	v_mov_b32_e32 v36, v32
	v_mov_b32_e32 v37, v32
	v_mov_b32_e32 v38, v32
	v_mov_b32_e32 v39, v32
	v_mov_b32_e32 v40, v32
	v_mov_b32_e32 v41, v32
	v_mov_b32_e32 v42, v32
	v_mov_b32_e32 v43, v32
	v_mov_b32_e32 v44, v32
	v_mov_b32_e32 v45, v32
	v_mov_b32_e32 v46, v32
	v_mov_b32_e32 v47, v32
	v_mov_b32_e32 v0, 0
	v_mov_b32_e32 v1, 0
	v_mov_b32_e32 v2, 0
	v_mov_b32_e32 v3, 0
	v_mov_b32_e32 v4, 0
	v_mov_b32_e32 v5, 0
	v_mov_b32_e32 v6, 0
	v_mov_b32_e32 v7, 0
	v_mov_b32_e32 v8, 0
	v_mov_b32_e32 v9, 0
	v_mov_b32_e32 v10, 0
	v_mov_b32_e32 v11, 0
	v_mov_b32_e32 v12, 0
	v_mov_b32_e32 v13, 0
	v_mov_b32_e32 v14, 0
	v_mov_b32_e32 v15, 0
	v_mov_b32_e32 v16, 0
	v_mov_b32_e32 v17, 0
	v_mov_b32_e32 v18, 0
	v_mov_b32_e32 v19, 0
	v_mov_b32_e32 v20, 0
	v_mov_b32_e32 v21, 0
	v_mov_b32_e32 v22, 0
	v_mov_b32_e32 v23, 0
	v_mov_b32_e32 v24, 0
	v_mov_b32_e32 v25, 0
	v_mov_b32_e32 v26, 0
	v_mov_b32_e32 v27, 0
	v_mov_b32_e32 v28, 0
	v_mov_b32_e32 v29, 0
	v_mov_b32_e32 v30, 0
	v_mov_b32_e32 v31, 0
	v_mov_b32_e32 v48, 0
	v_mov_b32_e32 v49, 0
	v_mov_b32_e32 v50, 0
	v_mov_b32_e32 v51, 0
	v_mov_b32_e32 v52, 0
	v_mov_b32_e32 v53, 0
	v_mov_b32_e32 v54, 0
	v_mov_b32_e32 v55, 0
	v_mov_b32_e32 v56, 0
	v_mov_b32_e32 v57, 0
	v_mov_b32_e32 v58, 0
	v_mov_b32_e32 v59, 0
	v_mov_b32_e32 v60, 0
	v_mov_b32_e32 v61, 0
	v_mov_b32_e32 v62, 0
	v_mov_b32_e32 v63, 0
	v_mov_b32_e32 v64, 0
	v_mov_b32_e32 v65, 0
	v_mov_b32_e32 v66, 0
	v_mov_b32_e32 v67, 0
	v_mov_b32_e32 v68, 0
	v_mov_b32_e32 v69, 0
	v_mov_b32_e32 v70, 0
	v_mov_b32_e32 v71, 0
	v_mov_b32_e32 v72, 0
	v_mov_b32_e32 v73, 0
	v_mov_b32_e32 v74, 0
	v_mov_b32_e32 v75, 0
	v_mov_b32_e32 v76, 0
	v_mov_b32_e32 v77, 0
	v_mov_b32_e32 v78, 0
	v_mov_b32_e32 v79, 0
	v_mov_b32_e32 v169, 0
	v_readlane_b32 s68, v251, 29
	v_readlane_b32 s69, v251, 30
	s_lshl_b32 s2, s26, 8
	s_add_u32 s68, s68, s2
	s_addc_u32 s69, s69, 0
	s_mov_b64 s[66:67], s[16:17]
	s_lshl_b32 s2, s10, 8
	s_add_i32 s65, s2, 0x8000
	s_lshl_b32 s2, s10, 13
	s_add_i32 s32, s2, 0xffffff00
	v_lshl_add_u32 v166, v136, 10, v168
	v_lshl_add_u32 v167, v134, 10, v140
	v_lshl_add_u32 v132, v144, 10, v140
	s_mov_b32 s70, 0
	s_cmp_lt_u32 s70, 4
	s_cselect_b32 s2, s65, s32
	s_lshl_b32 s3, s70, 6
	s_add_i32 s2, s2, s3
	s_lshl_b32 s2, s2, 10
	s_add_u32 s60, s66, s2
	s_addc_u32 s61, s67, 0
	s_cmp_lt_u32 s70, 4
	s_cselect_b32 s2, s65, s32
	s_lshl_b32 s3, s70, 6
	s_add_i32 s2, s2, s3
	s_lshl_b32 s2, s2, 10
	s_add_u32 s62, s68, s2
	s_addc_u32 s63, s69, 0
	global_load_dwordx4 v[234:237], v166, s[60:61]
	global_load_dwordx4 v[128:131], v167, s[62:63]
	global_load_dwordx4 v[170:173], v132, s[62:63]
	s_mov_b32 s70, 1
	s_cmp_lt_u32 s70, 4
	s_cselect_b32 s2, s65, s32
	s_lshl_b32 s3, s70, 6
	s_add_i32 s2, s2, s3
	s_lshl_b32 s2, s2, 10
	s_add_u32 s60, s66, s2
	s_addc_u32 s61, s67, 0
	global_load_dwordx4 v[198:201], v166, s[60:61]
	v_add_u32_e32 v248, v212, v139
	v_add_u32_e32 v249, v219, v140
	v_add_u32_e32 v133, v220, v140
	s_waitcnt vmcnt(0)
	ds_write_b128 v248, v[234:237]
	ds_write_b128 v248, v[198:201] offset:29696
	ds_write_b128 v249, v[128:131] offset:38912
	ds_write_b128 v133, v[170:173] offset:38912
	s_waitcnt lgkmcnt(0)
	s_barrier
; __device__ __forceinline__ unsigned cvt_pk_bf16(float lo, float hi) { f32x2 v = {lo, hi}; bf16x2_t b = __builtin_convertvector(v, bf16x2_t); return __builtin_bit_cast(unsigned, b); }
; template <int DV>
; __device__ __forceinline__ void attn_pass(const int tid, unsigned char* smem, const bf16_t* Q0, int qpitch, const bf16_t* Kb, int kpitch, const bf16_t* Vb, int vpitch,
;                                           int b, int ntiles, float kmax, f32x16 (&o)[DV / 32], float& linv) {
;     ...
;     for (int kt = 0; kt < ntiles; ++kt) {
;         if (kt + 1 < ntiles) gload(kt + 1);
;         const unsigned char* Ks = smem + (kt & 1) * BUF; const unsigned char* Vs = Ks + KBYTES;
;         const unsigned char* kp = Ks + r32 * KP + hi * 16;
;         bf16x8 pf[2][2];
; #pragma unroll
;         for (int kb = 0; kb < 2; ++kb) {
;             f32x16 s;
; #pragma unroll
;             for (int r = 0; r < 16; ++r) s[r] = nshift;
; #pragma unroll
;             for (int ds = 0; ds < 4; ++ds) {
;                 const bf16x8 kf = *(const bf16x8*)(kp + kb * 32 * KP + ds * 32);
;                 s = __builtin_amdgcn_mfma_f32_32x32x16_bf16(kf, qf[ds], s, 0, 0, 0);
;             }
;             float ls = 0.f;
; #pragma unroll
;             for (int r = 0; r < 16; ++r) { s[r] = __builtin_amdgcn_exp2f(s[r]); ls += s[r]; }
;             lsum += ls;
; #pragma unroll
;             for (int j = 0; j < 2; ++j) {
;                 u32x4 w0;
;                 w0.x = cvt_pk_bf16(s[8 * j + 0], s[8 * j + 1]); w0.y = cvt_pk_bf16(s[8 * j + 2], s[8 * j + 3]); w0.z = cvt_pk_bf16(s[8 * j + 4], s[8 * j + 5]); w0.w = cvt_pk_bf16(s[8 * j + 6], s[8 * j + 7]);
;                 pf[kb][j] = __builtin_bit_cast(bf16x8, w0);
;             }
;         }
	s_mov_b32 s56, 0
	s_movk_i32 s57, 0x7400
	s_mov_b32 s58, 0xe800
	s_mov_b32 s59, 0
	s_add_i32 s71, s25, -1
	s_add_i32 s70, s59, 2
	s_min_u32 s70, s70, s71
	s_cmp_lt_u32 s70, 4
	s_cselect_b32 s2, s65, s32
	s_lshl_b32 s3, s70, 6
	s_add_i32 s2, s2, s3
	s_lshl_b32 s2, s2, 10
	s_add_u32 s60, s66, s2
	s_addc_u32 s61, s67, 0
	s_add_i32 s70, s59, 1
	s_min_u32 s70, s70, s71
	s_cmp_lt_u32 s70, 4
	s_cselect_b32 s2, s65, s32
	s_lshl_b32 s3, s70, 6
	s_add_i32 s2, s2, s3
	s_lshl_b32 s2, s2, 10
	s_add_u32 s62, s68, s2
	s_addc_u32 s63, s69, 0
	global_load_dwordx4 v[234:237], v166, s[60:61]
	global_load_dwordx4 v[128:131], v167, s[62:63]
	global_load_dwordx4 v[170:173], v132, s[62:63]
	v_add_u32_e32 v174, v213, v138
	ds_read_b128 v[198:201], v174 offset:0
	ds_read_b128 v[202:205], v174 offset:32
	ds_read_b128 v[206:209], v174 offset:64
	ds_read_b128 v[150:153], v174 offset:96
	v_add3_u32 v174, s56, v213, v138
	v_add3_u32 v175, s56, v141, v221
	v_add3_u32 v210, s57, v213, v138
	v_add3_u32 v211, s57, v141, v221
	s_waitcnt lgkmcnt(3)
	v_mfma_f32_32x32x16_bf16 v[80:95], v[198:201], v[96:99], v[32:47]
	ds_read_b128 v[198:201], v174 offset:4608
	s_waitcnt lgkmcnt(3)
	v_mfma_f32_32x32x16_bf16 v[80:95], v[202:205], v[100:103], v[80:95]
	ds_read_b128 v[202:205], v174 offset:4640
	s_waitcnt lgkmcnt(3)
	v_mfma_f32_32x32x16_bf16 v[80:95], v[206:209], v[104:107], v[80:95]
	ds_read_b128 v[206:209], v174 offset:4672
	v_add3_u32 v248, s58, v212, v139
	v_add3_u32 v249, s58, v219, v140
	v_add3_u32 v133, s58, v220, v140
	s_waitcnt lgkmcnt(3)
	v_mfma_f32_32x32x16_bf16 v[80:95], v[150:153], v[108:111], v[80:95]
	ds_read_b128 v[150:153], v174 offset:4704
	s_nop 7
	s_waitcnt lgkmcnt(3)
	v_mfma_f32_32x32x16_bf16 v[112:127], v[198:201], v[96:99], v[32:47]
	ds_read_b128 v[198:201], v210 offset:0
	ds_read_b64_tr_b16 v[154:155], v211 offset:9216
	ds_read_b64_tr_b16 v[156:157], v211 offset:11776
	s_waitcnt vmcnt(0)
	ds_write_b128 v248, v[234:237]
	ds_write_b128 v249, v[128:131] offset:9216
	ds_write_b128 v133, v[170:173] offset:9216
	v_exp_f32_e32 v80, v80
	v_exp_f32_e32 v81, v81
	v_exp_f32_e32 v82, v82
	v_add_f32_e32 v169, v169, v80
	v_exp_f32_e32 v83, v83
	v_add_f32_e32 v169, v169, v81
	v_cvt_pk_bf16_f32 v176, v80, v81
	v_exp_f32_e32 v84, v84
	v_add_f32_e32 v169, v169, v82
	v_exp_f32_e32 v85, v85
	v_add_f32_e32 v169, v169, v83
	v_cvt_pk_bf16_f32 v177, v82, v83
	v_exp_f32_e32 v86, v86
	s_waitcnt lgkmcnt(8)
	v_mfma_f32_32x32x16_bf16 v[112:127], v[202:205], v[100:103], v[112:127]
	ds_read_b128 v[202:205], v210 offset:32
	ds_read_b64_tr_b16 v[158:159], v211 offset:9280
	ds_read_b64_tr_b16 v[160:161], v211 offset:11840
	s_add_i32 s71, s25, -1
	s_add_i32 s70, s59, 3
	s_min_u32 s70, s70, s71
	s_cmp_lt_u32 s70, 4
	s_cselect_b32 s2, s65, s32
	s_lshl_b32 s3, s70, 6
	s_add_i32 s2, s2, s3
	s_lshl_b32 s2, s2, 10
	s_add_u32 s60, s66, s2
	s_addc_u32 s61, s67, 0
	s_add_i32 s70, s59, 2
	s_min_u32 s70, s70, s71
	s_cmp_lt_u32 s70, 4
	s_cselect_b32 s2, s65, s32
	s_lshl_b32 s3, s70, 6
	s_add_i32 s2, s2, s3
	s_lshl_b32 s2, s2, 10
	s_add_u32 s62, s68, s2
	s_addc_u32 s63, s69, 0
	v_add_f32_e32 v169, v169, v84
	v_exp_f32_e32 v87, v87
	v_add_f32_e32 v169, v169, v85
	v_cvt_pk_bf16_f32 v178, v84, v85
	v_exp_f32_e32 v88, v88
	v_add_f32_e32 v169, v169, v86
	v_exp_f32_e32 v89, v89
	v_add_f32_e32 v169, v169, v87
	v_cvt_pk_bf16_f32 v179, v86, v87
	v_exp_f32_e32 v90, v90
	v_add_f32_e32 v169, v169, v88
	v_exp_f32_e32 v91, v91
	v_add_f32_e32 v169, v169, v89
	s_waitcnt lgkmcnt(10)
	v_mfma_f32_32x32x16_bf16 v[112:127], v[206:209], v[104:107], v[112:127]
	ds_read_b128 v[206:209], v210 offset:64
	ds_read_b64_tr_b16 v[162:163], v211 offset:9344
	ds_read_b64_tr_b16 v[164:165], v211 offset:11904
	global_load_dwordx4 v[234:237], v166, s[60:61]
	global_load_dwordx4 v[128:131], v167, s[62:63]
	global_load_dwordx4 v[170:173], v132, s[62:63]
	v_cvt_pk_bf16_f32 v180, v88, v89
	v_exp_f32_e32 v92, v92
	v_add_f32_e32 v169, v169, v90
	v_exp_f32_e32 v93, v93
	v_add_f32_e32 v169, v169, v91
	v_cvt_pk_bf16_f32 v181, v90, v91
	v_exp_f32_e32 v94, v94
	v_add_f32_e32 v169, v169, v92
	v_exp_f32_e32 v95, v95
	v_add_f32_e32 v169, v169, v93
	v_cvt_pk_bf16_f32 v182, v92, v93
	v_add_f32_e32 v169, v169, v94
	v_add_f32_e32 v169, v169, v95
	v_cvt_pk_bf16_f32 v183, v94, v95
	s_waitcnt lgkmcnt(12)
	v_mfma_f32_32x32x16_bf16 v[112:127], v[150:153], v[108:111], v[112:127]
	ds_read_b128 v[150:153], v210 offset:96
	ds_read_b64_tr_b16 v[230:231], v211 offset:9408
	ds_read_b64_tr_b16 v[232:233], v211 offset:11968
	v_add3_u32 v142, s57, v213, v138
	v_add3_u32 v143, s57, v141, v221
	v_add3_u32 v146, s58, v213, v138
	v_add3_u32 v147, s58, v141, v221
	s_mov_b32 s2, s56
	s_mov_b32 s56, s57
	s_mov_b32 s57, s58
	s_mov_b32 s58, s2
	s_add_i32 s59, s59, 1
	s_waitcnt lgkmcnt(0)
	s_barrier
; template <int DV>
; __device__ __forceinline__ void attn_pass(const int tid, unsigned char* smem, const bf16_t* Q0, int qpitch, const bf16_t* Kb, int kpitch, const bf16_t* Vb, int vpitch,
;                                           int b, int ntiles, float kmax, f32x16 (&o)[DV / 32], float& linv) {
;     ...
;     for (int kt = 0; kt < ntiles; ++kt) {
;         if (kt + 1 < ntiles) gload(kt + 1);
;         const unsigned char* Ks = smem + (kt & 1) * BUF; const unsigned char* Vs = Ks + KBYTES;
;         const unsigned char* kp = Ks + r32 * KP + hi * 16;
;         bf16x8 pf[2][2];
; #pragma unroll
;         for (int kb = 0; kb < 2; ++kb) {
;             f32x16 s;
; #pragma unroll
;             for (int r = 0; r < 16; ++r) s[r] = nshift;
; #pragma unroll
;             for (int ds = 0; ds < 4; ++ds) {
;                 const bf16x8 kf = *(const bf16x8*)(kp + kb * 32 * KP + ds * 32);
;                 s = __builtin_amdgcn_mfma_f32_32x32x16_bf16(kf, qf[ds], s, 0, 0, 0);
;             }
;             float ls = 0.f;
; #pragma unroll
;             for (int r = 0; r < 16; ++r) { s[r] = __builtin_amdgcn_exp2f(s[r]); ls += s[r]; }
;             lsum += ls;
; #pragma unroll
;             for (int j = 0; j < 2; ++j) {
;                 u32x4 w0;
;                 w0.x = cvt_pk_bf16(s[8 * j + 0], s[8 * j + 1]); w0.y = cvt_pk_bf16(s[8 * j + 2], s[8 * j + 3]); w0.z = cvt_pk_bf16(s[8 * j + 4], s[8 * j + 5]); w0.w = cvt_pk_bf16(s[8 * j + 6], s[8 * j + 7]);
;                 pf[kb][j] = __builtin_bit_cast(bf16x8, w0);
;             }
;         }
;         const unsigned char* vp = Vs + (4 * hi + q4) * VP + (16 * nhalf + 4 * p4) * 2;
; #pragma unroll
;         for (int d0 = 0; d0 < DV / 32; ++d0) {
; #pragma unroll
;             for (int kb = 0; kb < 2; ++kb)
; #pragma unroll
;                 for (int j = 0; j < 2; ++j) {
;                     const unsigned char* a = vp + (32 * kb + 16 * j) * VP + d0 * 64;
;                     const s16x4 lo = ld_tr(a), h4 = ld_tr(a + 8 * VP);
;                     const bf16x8 vf = (bf16x8){lo[0], lo[1], lo[2], lo[3], h4[0], h4[1], h4[2], h4[3]};
;                     o[d0] = __builtin_amdgcn_mfma_f32_32x32x16_bf16(vf, pf[kb][j], o[d0], 0, 0, 0);
;                 }
;             if (d0 & 1) __builtin_amdgcn_sched_barrier(0);
;         }
;         if (kt + 1 < ntiles) lwrite((kt + 1) & 1);
;         __syncthreads();
.Lcattn_loop:
	v_mfma_f32_32x32x16_bf16 v[80:95], v[198:201], v[96:99], v[32:47]
	ds_read_b128 v[198:201], v142 offset:4608
	v_exp_f32_e32 v112, v112
	v_exp_f32_e32 v113, v113
	v_exp_f32_e32 v114, v114
	v_mfma_f32_32x32x16_bf16 v[80:95], v[202:205], v[100:103], v[80:95]
	ds_read_b128 v[202:205], v142 offset:4640
	v_add_f32_e32 v169, v169, v112
	v_exp_f32_e32 v115, v115
	v_add_f32_e32 v169, v169, v113
	v_cvt_pk_bf16_f32 v184, v112, v113
	v_mfma_f32_32x32x16_bf16 v[80:95], v[206:209], v[104:107], v[80:95]
	ds_read_b128 v[206:209], v142 offset:4672
	v_exp_f32_e32 v116, v116
	v_add_f32_e32 v169, v169, v114
	v_exp_f32_e32 v117, v117
	v_mfma_f32_32x32x16_bf16 v[80:95], v[150:153], v[108:111], v[80:95]
	ds_read_b128 v[150:153], v142 offset:4704
	v_add_f32_e32 v169, v169, v115
	v_cvt_pk_bf16_f32 v185, v114, v115
	v_exp_f32_e32 v118, v118
	v_add_f32_e32 v169, v169, v116
	s_waitcnt lgkmcnt(10)
	v_mfma_f32_32x32x16_bf16 v[0:15], v[154:157], v[176:179], v[0:15]
	ds_read_b64_tr_b16 v[154:155], v143 offset:14336
	ds_read_b64_tr_b16 v[156:157], v143 offset:16896
	v_exp_f32_e32 v119, v119
	v_add_f32_e32 v169, v169, v117
	v_cvt_pk_bf16_f32 v186, v116, v117
	v_exp_f32_e32 v120, v120
	s_waitcnt lgkmcnt(10)
	v_mfma_f32_32x32x16_bf16 v[16:31], v[158:161], v[176:179], v[16:31]
	ds_read_b64_tr_b16 v[158:159], v143 offset:14400
	ds_read_b64_tr_b16 v[160:161], v143 offset:16960
	v_add_f32_e32 v169, v169, v118
	v_exp_f32_e32 v121, v121
	v_add_f32_e32 v169, v169, v119
	s_waitcnt lgkmcnt(10)
	v_mfma_f32_32x32x16_bf16 v[48:63], v[162:165], v[176:179], v[48:63]
	ds_read_b64_tr_b16 v[162:163], v143 offset:14464
	ds_read_b64_tr_b16 v[164:165], v143 offset:17024
	v_add3_u32 v248, s58, v212, v139
	v_add3_u32 v249, s58, v219, v140
	v_add3_u32 v133, s58, v220, v140
	v_cvt_pk_bf16_f32 v187, v118, v119
	v_exp_f32_e32 v122, v122
	v_add_f32_e32 v169, v169, v120
	v_exp_f32_e32 v123, v123
	s_waitcnt lgkmcnt(10)
	v_mfma_f32_32x32x16_bf16 v[64:79], v[230:233], v[176:179], v[64:79]
	ds_read_b64_tr_b16 v[230:231], v143 offset:14528
	ds_read_b64_tr_b16 v[232:233], v143 offset:17088
	v_add_f32_e32 v169, v169, v121
	v_cvt_pk_bf16_f32 v188, v120, v121
	v_exp_f32_e32 v124, v124
	s_waitcnt lgkmcnt(6)
	v_mfma_f32_32x32x16_bf16 v[0:15], v[154:157], v[180:183], v[0:15]
	ds_read_b64_tr_b16 v[154:155], v143 offset:19456
	ds_read_b64_tr_b16 v[156:157], v143 offset:22016
	v_add_f32_e32 v169, v169, v122
	v_exp_f32_e32 v125, v125
	v_add_f32_e32 v169, v169, v123
	v_cvt_pk_bf16_f32 v189, v122, v123
	s_waitcnt lgkmcnt(6)
	v_mfma_f32_32x32x16_bf16 v[16:31], v[158:161], v[180:183], v[16:31]
	ds_read_b64_tr_b16 v[158:159], v143 offset:19520
	ds_read_b64_tr_b16 v[160:161], v143 offset:22080
	v_exp_f32_e32 v126, v126
	v_add_f32_e32 v169, v169, v124
	v_exp_f32_e32 v127, v127
	s_waitcnt lgkmcnt(6)
	v_mfma_f32_32x32x16_bf16 v[48:63], v[162:165], v[180:183], v[48:63]
	ds_read_b64_tr_b16 v[162:163], v143 offset:19584
	ds_read_b64_tr_b16 v[164:165], v143 offset:22144
	v_add_f32_e32 v169, v169, v125
	v_cvt_pk_bf16_f32 v190, v124, v125
	v_add_f32_e32 v169, v169, v126
	v_add_f32_e32 v169, v169, v127
	v_cvt_pk_bf16_f32 v191, v126, v127
	s_waitcnt lgkmcnt(6)
	v_mfma_f32_32x32x16_bf16 v[64:79], v[230:233], v[180:183], v[64:79]
	ds_read_b64_tr_b16 v[230:231], v143 offset:19648
	ds_read_b64_tr_b16 v[232:233], v143 offset:22208
	v_mfma_f32_32x32x16_bf16 v[112:127], v[198:201], v[96:99], v[32:47]
	ds_read_b128 v[198:201], v146 offset:0
	v_exp_f32_e32 v80, v80
	v_exp_f32_e32 v81, v81
	v_exp_f32_e32 v82, v82
	v_mfma_f32_32x32x16_bf16 v[112:127], v[202:205], v[100:103], v[112:127]
	ds_read_b128 v[202:205], v146 offset:32
	v_add_f32_e32 v169, v169, v80
	v_exp_f32_e32 v83, v83
	v_add_f32_e32 v169, v169, v81
	v_cvt_pk_bf16_f32 v176, v80, v81
	v_mfma_f32_32x32x16_bf16 v[112:127], v[206:209], v[104:107], v[112:127]
	ds_read_b128 v[206:209], v146 offset:64
	v_exp_f32_e32 v84, v84
	v_add_f32_e32 v169, v169, v82
	v_exp_f32_e32 v85, v85
	v_mfma_f32_32x32x16_bf16 v[112:127], v[150:153], v[108:111], v[112:127]
	ds_read_b128 v[150:153], v146 offset:96
	v_add_f32_e32 v169, v169, v83
	v_cvt_pk_bf16_f32 v177, v82, v83
	v_exp_f32_e32 v86, v86
	v_add_f32_e32 v169, v169, v84
	s_waitcnt lgkmcnt(10)
	v_mfma_f32_32x32x16_bf16 v[0:15], v[154:157], v[184:187], v[0:15]
	ds_read_b64_tr_b16 v[154:155], v143 offset:24576
	ds_read_b64_tr_b16 v[156:157], v143 offset:27136
	s_waitcnt vmcnt(0)
	ds_write_b128 v248, v[234:237]
	v_exp_f32_e32 v87, v87
	v_add_f32_e32 v169, v169, v85
	v_cvt_pk_bf16_f32 v178, v84, v85
	v_exp_f32_e32 v88, v88
	s_waitcnt lgkmcnt(11)
	v_mfma_f32_32x32x16_bf16 v[16:31], v[158:161], v[184:187], v[16:31]
	ds_read_b64_tr_b16 v[158:159], v143 offset:24640
	ds_read_b64_tr_b16 v[160:161], v143 offset:27200
	ds_write_b128 v249, v[128:131] offset:9216
	v_add_f32_e32 v169, v169, v86
	v_exp_f32_e32 v89, v89
	v_add_f32_e32 v169, v169, v87
	s_waitcnt lgkmcnt(12)
	v_mfma_f32_32x32x16_bf16 v[48:63], v[162:165], v[184:187], v[48:63]
	ds_read_b64_tr_b16 v[162:163], v143 offset:24704
	ds_read_b64_tr_b16 v[164:165], v143 offset:27264
	ds_write_b128 v133, v[170:173] offset:9216
	v_cvt_pk_bf16_f32 v179, v86, v87
	v_exp_f32_e32 v90, v90
	v_add_f32_e32 v169, v169, v88
	v_exp_f32_e32 v91, v91
	s_waitcnt lgkmcnt(13)
	v_mfma_f32_32x32x16_bf16 v[64:79], v[230:233], v[184:187], v[64:79]
	ds_read_b64_tr_b16 v[230:231], v143 offset:24768
	ds_read_b64_tr_b16 v[232:233], v143 offset:27328
	s_add_i32 s71, s25, -1
	s_add_i32 s70, s59, 3
	s_min_u32 s70, s70, s71
	s_cmp_lt_u32 s70, 4
	s_cselect_b32 s2, s65, s32
	s_lshl_b32 s3, s70, 6
	s_add_i32 s2, s2, s3
	s_lshl_b32 s2, s2, 10
	s_add_u32 s60, s66, s2
	s_addc_u32 s61, s67, 0
	s_add_i32 s70, s59, 2
	s_min_u32 s70, s70, s71
	s_cmp_lt_u32 s70, 4
	s_cselect_b32 s2, s65, s32
	s_lshl_b32 s3, s70, 6
	s_add_i32 s2, s2, s3
	s_lshl_b32 s2, s2, 10
	s_add_u32 s62, s68, s2
	s_addc_u32 s63, s69, 0
	v_add_f32_e32 v169, v169, v89
	v_cvt_pk_bf16_f32 v180, v88, v89
	v_exp_f32_e32 v92, v92
	s_waitcnt lgkmcnt(9)
; template <int DV>
; __device__ __forceinline__ void attn_pass(const int tid, unsigned char* smem, const bf16_t* Q0, int qpitch, const bf16_t* Kb, int kpitch, const bf16_t* Vb, int vpitch,
;                                           int b, int ntiles, float kmax, f32x16 (&o)[DV / 32], float& linv) {
;     ...
;     for (int kt = 0; kt < ntiles; ++kt) {
;         if (kt + 1 < ntiles) gload(kt + 1);
;         const unsigned char* Ks = smem + (kt & 1) * BUF; const unsigned char* Vs = Ks + KBYTES;
;         const unsigned char* kp = Ks + r32 * KP + hi * 16;
;         bf16x8 pf[2][2];
; #pragma unroll
;         for (int kb = 0; kb < 2; ++kb) {
;             f32x16 s;
; #pragma unroll
;             for (int r = 0; r < 16; ++r) s[r] = nshift;
; #pragma unroll
;             for (int ds = 0; ds < 4; ++ds) {
;                 const bf16x8 kf = *(const bf16x8*)(kp + kb * 32 * KP + ds * 32);
;                 s = __builtin_amdgcn_mfma_f32_32x32x16_bf16(kf, qf[ds], s, 0, 0, 0);
;             }
;             float ls = 0.f;
; #pragma unroll
;             for (int r = 0; r < 16; ++r) { s[r] = __builtin_amdgcn_exp2f(s[r]); ls += s[r]; }
;             lsum += ls;
; #pragma unroll
;             for (int j = 0; j < 2; ++j) {
;                 u32x4 w0;
;                 w0.x = cvt_pk_bf16(s[8 * j + 0], s[8 * j + 1]); w0.y = cvt_pk_bf16(s[8 * j + 2], s[8 * j + 3]); w0.z = cvt_pk_bf16(s[8 * j + 4], s[8 * j + 5]); w0.w = cvt_pk_bf16(s[8 * j + 6], s[8 * j + 7]);
;                 pf[kb][j] = __builtin_bit_cast(bf16x8, w0);
;             }
;         }
;         const unsigned char* vp = Vs + (4 * hi + q4) * VP + (16 * nhalf + 4 * p4) * 2;
; #pragma unroll
;         for (int d0 = 0; d0 < DV / 32; ++d0) {
; #pragma unroll
;             for (int kb = 0; kb < 2; ++kb)
; #pragma unroll
;                 for (int j = 0; j < 2; ++j) {
;                     const unsigned char* a = vp + (32 * kb + 16 * j) * VP + d0 * 64;
;                     const s16x4 lo = ld_tr(a), h4 = ld_tr(a + 8 * VP);
;                     const bf16x8 vf = (bf16x8){lo[0], lo[1], lo[2], lo[3], h4[0], h4[1], h4[2], h4[3]};
;                     o[d0] = __builtin_amdgcn_mfma_f32_32x32x16_bf16(vf, pf[kb][j], o[d0], 0, 0, 0);
;                 }
;             if (d0 & 1) __builtin_amdgcn_sched_barrier(0);
;         }
;         if (kt + 1 < ntiles) lwrite((kt + 1) & 1);
;         __syncthreads();
	v_mfma_f32_32x32x16_bf16 v[0:15], v[154:157], v[188:191], v[0:15]
	ds_read_b64_tr_b16 v[154:155], v147 offset:9216
	ds_read_b64_tr_b16 v[156:157], v147 offset:11776
	global_load_dwordx4 v[234:237], v166, s[60:61]
	global_load_dwordx4 v[128:131], v167, s[62:63]
	global_load_dwordx4 v[170:173], v132, s[62:63]
	v_add_f32_e32 v169, v169, v90
	v_exp_f32_e32 v93, v93
	v_add_f32_e32 v169, v169, v91
	v_cvt_pk_bf16_f32 v181, v90, v91
	s_waitcnt lgkmcnt(8)
	v_mfma_f32_32x32x16_bf16 v[16:31], v[158:161], v[188:191], v[16:31]
	ds_read_b64_tr_b16 v[158:159], v147 offset:9280
	ds_read_b64_tr_b16 v[160:161], v147 offset:11840
	v_add3_u32 v174, s57, v213, v138
	v_add3_u32 v175, s57, v141, v221
	v_add3_u32 v210, s58, v213, v138
	v_add3_u32 v211, s58, v141, v221
	v_exp_f32_e32 v94, v94
	v_add_f32_e32 v169, v169, v92
	v_exp_f32_e32 v95, v95
	s_waitcnt lgkmcnt(7)
	v_mfma_f32_32x32x16_bf16 v[48:63], v[162:165], v[188:191], v[48:63]
	ds_read_b64_tr_b16 v[162:163], v147 offset:9344
	ds_read_b64_tr_b16 v[164:165], v147 offset:11904
	s_mov_b32 s2, s56
	s_mov_b32 s56, s57
	s_mov_b32 s57, s58
	s_mov_b32 s58, s2
	s_add_i32 s59, s59, 1
	v_add_f32_e32 v169, v169, v93
	v_cvt_pk_bf16_f32 v182, v92, v93
	v_add_f32_e32 v169, v169, v94
	v_add_f32_e32 v169, v169, v95
	v_cvt_pk_bf16_f32 v183, v94, v95
	s_waitcnt lgkmcnt(6)
	v_mfma_f32_32x32x16_bf16 v[64:79], v[230:233], v[188:191], v[64:79]
	ds_read_b64_tr_b16 v[230:231], v147 offset:9408
	ds_read_b64_tr_b16 v[232:233], v147 offset:11968
	s_waitcnt lgkmcnt(10)
	s_barrier
	v_mfma_f32_32x32x16_bf16 v[80:95], v[198:201], v[96:99], v[32:47]
	ds_read_b128 v[198:201], v174 offset:4608
	v_exp_f32_e32 v112, v112
	v_exp_f32_e32 v113, v113
	v_exp_f32_e32 v114, v114
	v_mfma_f32_32x32x16_bf16 v[80:95], v[202:205], v[100:103], v[80:95]
	ds_read_b128 v[202:205], v174 offset:4640
	v_add_f32_e32 v169, v169, v112
	v_exp_f32_e32 v115, v115
	v_add_f32_e32 v169, v169, v113
	v_cvt_pk_bf16_f32 v184, v112, v113
	v_mfma_f32_32x32x16_bf16 v[80:95], v[206:209], v[104:107], v[80:95]
	ds_read_b128 v[206:209], v174 offset:4672
	v_exp_f32_e32 v116, v116
	v_add_f32_e32 v169, v169, v114
	v_exp_f32_e32 v117, v117
	v_mfma_f32_32x32x16_bf16 v[80:95], v[150:153], v[108:111], v[80:95]
	ds_read_b128 v[150:153], v174 offset:4704
	v_add_f32_e32 v169, v169, v115
	v_cvt_pk_bf16_f32 v185, v114, v115
	v_exp_f32_e32 v118, v118
	v_add_f32_e32 v169, v169, v116
	s_waitcnt lgkmcnt(10)
	v_mfma_f32_32x32x16_bf16 v[0:15], v[154:157], v[176:179], v[0:15]
	ds_read_b64_tr_b16 v[154:155], v175 offset:14336
	ds_read_b64_tr_b16 v[156:157], v175 offset:16896
	v_exp_f32_e32 v119, v119
	v_add_f32_e32 v169, v169, v117
	v_cvt_pk_bf16_f32 v186, v116, v117
	v_exp_f32_e32 v120, v120
	s_waitcnt lgkmcnt(10)
	v_mfma_f32_32x32x16_bf16 v[16:31], v[158:161], v[176:179], v[16:31]
	ds_read_b64_tr_b16 v[158:159], v175 offset:14400
	ds_read_b64_tr_b16 v[160:161], v175 offset:16960
	v_add_f32_e32 v169, v169, v118
	v_exp_f32_e32 v121, v121
	v_add_f32_e32 v169, v169, v119
	s_waitcnt lgkmcnt(10)
	v_mfma_f32_32x32x16_bf16 v[48:63], v[162:165], v[176:179], v[48:63]
	ds_read_b64_tr_b16 v[162:163], v175 offset:14464
	ds_read_b64_tr_b16 v[164:165], v175 offset:17024
	v_add3_u32 v248, s58, v212, v139
	v_add3_u32 v249, s58, v219, v140
	v_add3_u32 v133, s58, v220, v140
	v_cvt_pk_bf16_f32 v187, v118, v119
	v_exp_f32_e32 v122, v122
	v_add_f32_e32 v169, v169, v120
	v_exp_f32_e32 v123, v123
	s_waitcnt lgkmcnt(10)
	v_mfma_f32_32x32x16_bf16 v[64:79], v[230:233], v[176:179], v[64:79]
	ds_read_b64_tr_b16 v[230:231], v175 offset:14528
	ds_read_b64_tr_b16 v[232:233], v175 offset:17088
	v_add_f32_e32 v169, v169, v121
	v_cvt_pk_bf16_f32 v188, v120, v121
	v_exp_f32_e32 v124, v124
	s_waitcnt lgkmcnt(6)
	v_mfma_f32_32x32x16_bf16 v[0:15], v[154:157], v[180:183], v[0:15]
	ds_read_b64_tr_b16 v[154:155], v175 offset:19456
	ds_read_b64_tr_b16 v[156:157], v175 offset:22016
	v_add_f32_e32 v169, v169, v122
	v_exp_f32_e32 v125, v125
	v_add_f32_e32 v169, v169, v123
	v_cvt_pk_bf16_f32 v189, v122, v123
	s_waitcnt lgkmcnt(6)
	v_mfma_f32_32x32x16_bf16 v[16:31], v[158:161], v[180:183], v[16:31]
	ds_read_b64_tr_b16 v[158:159], v175 offset:19520
	ds_read_b64_tr_b16 v[160:161], v175 offset:22080
	v_exp_f32_e32 v126, v126
	v_add_f32_e32 v169, v169, v124
	v_exp_f32_e32 v127, v127
	s_waitcnt lgkmcnt(6)
	v_mfma_f32_32x32x16_bf16 v[48:63], v[162:165], v[180:183], v[48:63]
	ds_read_b64_tr_b16 v[162:163], v175 offset:19584
	ds_read_b64_tr_b16 v[164:165], v175 offset:22144
	v_add_f32_e32 v169, v169, v125
	v_cvt_pk_bf16_f32 v190, v124, v125
	v_add_f32_e32 v169, v169, v126
	v_add_f32_e32 v169, v169, v127
	v_cvt_pk_bf16_f32 v191, v126, v127
	s_waitcnt lgkmcnt(6)
	v_mfma_f32_32x32x16_bf16 v[64:79], v[230:233], v[180:183], v[64:79]
	ds_read_b64_tr_b16 v[230:231], v175 offset:19648
	ds_read_b64_tr_b16 v[232:233], v175 offset:22208
	v_mfma_f32_32x32x16_bf16 v[112:127], v[198:201], v[96:99], v[32:47]
	ds_read_b128 v[198:201], v210 offset:0
	v_exp_f32_e32 v80, v80
	v_exp_f32_e32 v81, v81
	v_exp_f32_e32 v82, v82
	v_mfma_f32_32x32x16_bf16 v[112:127], v[202:205], v[100:103], v[112:127]
	ds_read_b128 v[202:205], v210 offset:32
	v_add_f32_e32 v169, v169, v80
	v_exp_f32_e32 v83, v83
	v_add_f32_e32 v169, v169, v81
	v_cvt_pk_bf16_f32 v176, v80, v81
	v_mfma_f32_32x32x16_bf16 v[112:127], v[206:209], v[104:107], v[112:127]
	ds_read_b128 v[206:209], v210 offset:64
	v_exp_f32_e32 v84, v84
	v_add_f32_e32 v169, v169, v82
	v_exp_f32_e32 v85, v85
	v_mfma_f32_32x32x16_bf16 v[112:127], v[150:153], v[108:111], v[112:127]
	ds_read_b128 v[150:153], v210 offset:96
	v_add_f32_e32 v169, v169, v83
	v_cvt_pk_bf16_f32 v177, v82, v83
	v_exp_f32_e32 v86, v86
	v_add_f32_e32 v169, v169, v84
	s_waitcnt lgkmcnt(10)
; template <int DV>
; __device__ __forceinline__ void attn_pass(const int tid, unsigned char* smem, const bf16_t* Q0, int qpitch, const bf16_t* Kb, int kpitch, const bf16_t* Vb, int vpitch,
;                                           int b, int ntiles, float kmax, f32x16 (&o)[DV / 32], float& linv) {
;     ...
;     for (int kt = 0; kt < ntiles; ++kt) {
;         if (kt + 1 < ntiles) gload(kt + 1);
;         const unsigned char* Ks = smem + (kt & 1) * BUF; const unsigned char* Vs = Ks + KBYTES;
;         const unsigned char* kp = Ks + r32 * KP + hi * 16;
;         bf16x8 pf[2][2];
; #pragma unroll
;         for (int kb = 0; kb < 2; ++kb) {
;             f32x16 s;
; #pragma unroll
;             for (int r = 0; r < 16; ++r) s[r] = nshift;
; #pragma unroll
;             for (int ds = 0; ds < 4; ++ds) {
;                 const bf16x8 kf = *(const bf16x8*)(kp + kb * 32 * KP + ds * 32);
;                 s = __builtin_amdgcn_mfma_f32_32x32x16_bf16(kf, qf[ds], s, 0, 0, 0);
;             }
;             float ls = 0.f;
; #pragma unroll
;             for (int r = 0; r < 16; ++r) { s[r] = __builtin_amdgcn_exp2f(s[r]); ls += s[r]; }
;             lsum += ls;
; #pragma unroll
;             for (int j = 0; j < 2; ++j) {
;                 u32x4 w0;
;                 w0.x = cvt_pk_bf16(s[8 * j + 0], s[8 * j + 1]); w0.y = cvt_pk_bf16(s[8 * j + 2], s[8 * j + 3]); w0.z = cvt_pk_bf16(s[8 * j + 4], s[8 * j + 5]); w0.w = cvt_pk_bf16(s[8 * j + 6], s[8 * j + 7]);
;                 pf[kb][j] = __builtin_bit_cast(bf16x8, w0);
;             }
;         }
;         const unsigned char* vp = Vs + (4 * hi + q4) * VP + (16 * nhalf + 4 * p4) * 2;
; #pragma unroll
;         for (int d0 = 0; d0 < DV / 32; ++d0) {
; #pragma unroll
;             for (int kb = 0; kb < 2; ++kb)
; #pragma unroll
;                 for (int j = 0; j < 2; ++j) {
;                     const unsigned char* a = vp + (32 * kb + 16 * j) * VP + d0 * 64;
;                     const s16x4 lo = ld_tr(a), h4 = ld_tr(a + 8 * VP);
;                     const bf16x8 vf = (bf16x8){lo[0], lo[1], lo[2], lo[3], h4[0], h4[1], h4[2], h4[3]};
;                     o[d0] = __builtin_amdgcn_mfma_f32_32x32x16_bf16(vf, pf[kb][j], o[d0], 0, 0, 0);
;                 }
;             if (d0 & 1) __builtin_amdgcn_sched_barrier(0);
;         }
;         if (kt + 1 < ntiles) lwrite((kt + 1) & 1);
;         __syncthreads();
	v_mfma_f32_32x32x16_bf16 v[0:15], v[154:157], v[184:187], v[0:15]
	ds_read_b64_tr_b16 v[154:155], v175 offset:24576
	ds_read_b64_tr_b16 v[156:157], v175 offset:27136
	s_waitcnt vmcnt(0)
	ds_write_b128 v248, v[234:237]
	v_exp_f32_e32 v87, v87
	v_add_f32_e32 v169, v169, v85
	v_cvt_pk_bf16_f32 v178, v84, v85
	v_exp_f32_e32 v88, v88
	s_waitcnt lgkmcnt(11)
	v_mfma_f32_32x32x16_bf16 v[16:31], v[158:161], v[184:187], v[16:31]
	ds_read_b64_tr_b16 v[158:159], v175 offset:24640
	ds_read_b64_tr_b16 v[160:161], v175 offset:27200
	ds_write_b128 v249, v[128:131] offset:9216
	v_add_f32_e32 v169, v169, v86
	v_exp_f32_e32 v89, v89
	v_add_f32_e32 v169, v169, v87
	s_waitcnt lgkmcnt(12)
	v_mfma_f32_32x32x16_bf16 v[48:63], v[162:165], v[184:187], v[48:63]
	ds_read_b64_tr_b16 v[162:163], v175 offset:24704
	ds_read_b64_tr_b16 v[164:165], v175 offset:27264
	ds_write_b128 v133, v[170:173] offset:9216
	v_cvt_pk_bf16_f32 v179, v86, v87
	v_exp_f32_e32 v90, v90
	v_add_f32_e32 v169, v169, v88
	v_exp_f32_e32 v91, v91
	s_waitcnt lgkmcnt(13)
	v_mfma_f32_32x32x16_bf16 v[64:79], v[230:233], v[184:187], v[64:79]
	ds_read_b64_tr_b16 v[230:231], v175 offset:24768
	ds_read_b64_tr_b16 v[232:233], v175 offset:27328
	s_add_i32 s71, s25, -1
	s_add_i32 s70, s59, 3
	s_min_u32 s70, s70, s71
	s_cmp_lt_u32 s70, 4
	s_cselect_b32 s2, s65, s32
	s_lshl_b32 s3, s70, 6
	s_add_i32 s2, s2, s3
	s_lshl_b32 s2, s2, 10
	s_add_u32 s60, s66, s2
	s_addc_u32 s61, s67, 0
	s_add_i32 s70, s59, 2
	s_min_u32 s70, s70, s71
	s_cmp_lt_u32 s70, 4
	s_cselect_b32 s2, s65, s32
	s_lshl_b32 s3, s70, 6
	s_add_i32 s2, s2, s3
	s_lshl_b32 s2, s2, 10
	s_add_u32 s62, s68, s2
	s_addc_u32 s63, s69, 0
	v_add_f32_e32 v169, v169, v89
	v_cvt_pk_bf16_f32 v180, v88, v89
	v_exp_f32_e32 v92, v92
	s_waitcnt lgkmcnt(9)
	v_mfma_f32_32x32x16_bf16 v[0:15], v[154:157], v[188:191], v[0:15]
	ds_read_b64_tr_b16 v[154:155], v211 offset:9216
	ds_read_b64_tr_b16 v[156:157], v211 offset:11776
	global_load_dwordx4 v[234:237], v166, s[60:61]
	global_load_dwordx4 v[128:131], v167, s[62:63]
	global_load_dwordx4 v[170:173], v132, s[62:63]
	v_add_f32_e32 v169, v169, v90
	v_exp_f32_e32 v93, v93
	v_add_f32_e32 v169, v169, v91
	v_cvt_pk_bf16_f32 v181, v90, v91
	s_waitcnt lgkmcnt(8)
	v_mfma_f32_32x32x16_bf16 v[16:31], v[158:161], v[188:191], v[16:31]
	ds_read_b64_tr_b16 v[158:159], v211 offset:9280
	ds_read_b64_tr_b16 v[160:161], v211 offset:11840
	v_add3_u32 v142, s57, v213, v138
	v_add3_u32 v143, s57, v141, v221
	v_add3_u32 v146, s58, v213, v138
	v_add3_u32 v147, s58, v141, v221
	v_exp_f32_e32 v94, v94
	v_add_f32_e32 v169, v169, v92
	v_exp_f32_e32 v95, v95
	s_waitcnt lgkmcnt(7)
	v_mfma_f32_32x32x16_bf16 v[48:63], v[162:165], v[188:191], v[48:63]
	ds_read_b64_tr_b16 v[162:163], v211 offset:9344
	ds_read_b64_tr_b16 v[164:165], v211 offset:11904
	s_mov_b32 s2, s56
	s_mov_b32 s56, s57
	s_mov_b32 s57, s58
	s_mov_b32 s58, s2
	s_add_i32 s59, s59, 1
	v_add_f32_e32 v169, v169, v93
	v_cvt_pk_bf16_f32 v182, v92, v93
	v_add_f32_e32 v169, v169, v94
	v_add_f32_e32 v169, v169, v95
	v_cvt_pk_bf16_f32 v183, v94, v95
	s_waitcnt lgkmcnt(6)
	v_mfma_f32_32x32x16_bf16 v[64:79], v[230:233], v[188:191], v[64:79]
	ds_read_b64_tr_b16 v[230:231], v211 offset:9408
	ds_read_b64_tr_b16 v[232:233], v211 offset:11968
	s_add_i32 s71, s25, -1
	s_cmp_lt_u32 s59, s71
	s_waitcnt lgkmcnt(10)
	s_barrier
	s_cbranch_scc1 .Lcattn_loop
	v_mfma_f32_32x32x16_bf16 v[80:95], v[198:201], v[96:99], v[32:47]
	ds_read_b128 v[198:201], v142 offset:4608
	v_exp_f32_e32 v112, v112
	v_exp_f32_e32 v113, v113
	v_exp_f32_e32 v114, v114
	v_mfma_f32_32x32x16_bf16 v[80:95], v[202:205], v[100:103], v[80:95]
	ds_read_b128 v[202:205], v142 offset:4640
	v_add_f32_e32 v169, v169, v112
	v_exp_f32_e32 v115, v115
	v_add_f32_e32 v169, v169, v113
	v_cvt_pk_bf16_f32 v184, v112, v113
	v_mfma_f32_32x32x16_bf16 v[80:95], v[206:209], v[104:107], v[80:95]
	ds_read_b128 v[206:209], v142 offset:4672
	v_exp_f32_e32 v116, v116
	v_add_f32_e32 v169, v169, v114
	v_exp_f32_e32 v117, v117
	v_mfma_f32_32x32x16_bf16 v[80:95], v[150:153], v[108:111], v[80:95]
	ds_read_b128 v[150:153], v142 offset:4704
	v_add_f32_e32 v169, v169, v115
	v_cvt_pk_bf16_f32 v185, v114, v115
	v_exp_f32_e32 v118, v118
	v_add_f32_e32 v169, v169, v116
	s_waitcnt lgkmcnt(10)
	v_mfma_f32_32x32x16_bf16 v[0:15], v[154:157], v[176:179], v[0:15]
	ds_read_b64_tr_b16 v[154:155], v143 offset:14336
	ds_read_b64_tr_b16 v[156:157], v143 offset:16896
	v_exp_f32_e32 v119, v119
	v_add_f32_e32 v169, v169, v117
	v_cvt_pk_bf16_f32 v186, v116, v117
	v_exp_f32_e32 v120, v120
	s_waitcnt lgkmcnt(10)
	v_mfma_f32_32x32x16_bf16 v[16:31], v[158:161], v[176:179], v[16:31]
	ds_read_b64_tr_b16 v[158:159], v143 offset:14400
	ds_read_b64_tr_b16 v[160:161], v143 offset:16960
	v_add_f32_e32 v169, v169, v118
	v_exp_f32_e32 v121, v121
	v_add_f32_e32 v169, v169, v119
	s_waitcnt lgkmcnt(10)
	v_mfma_f32_32x32x16_bf16 v[48:63], v[162:165], v[176:179], v[48:63]
	ds_read_b64_tr_b16 v[162:163], v143 offset:14464
	ds_read_b64_tr_b16 v[164:165], v143 offset:17024
	v_cvt_pk_bf16_f32 v187, v118, v119
	v_exp_f32_e32 v122, v122
	v_add_f32_e32 v169, v169, v120
	v_exp_f32_e32 v123, v123
	s_waitcnt lgkmcnt(10)
	v_mfma_f32_32x32x16_bf16 v[64:79], v[230:233], v[176:179], v[64:79]
	ds_read_b64_tr_b16 v[230:231], v143 offset:14528
	ds_read_b64_tr_b16 v[232:233], v143 offset:17088
	v_add_f32_e32 v169, v169, v121
	v_cvt_pk_bf16_f32 v188, v120, v121
	v_exp_f32_e32 v124, v124
	s_waitcnt lgkmcnt(6)
	v_mfma_f32_32x32x16_bf16 v[0:15], v[154:157], v[180:183], v[0:15]
	ds_read_b64_tr_b16 v[154:155], v143 offset:19456
	ds_read_b64_tr_b16 v[156:157], v143 offset:22016
	v_add_f32_e32 v169, v169, v122
	v_exp_f32_e32 v125, v125
	v_add_f32_e32 v169, v169, v123
	v_cvt_pk_bf16_f32 v189, v122, v123
	s_waitcnt lgkmcnt(6)
; template <int DV>
; __device__ __forceinline__ void attn_pass(const int tid, unsigned char* smem, const bf16_t* Q0, int qpitch, const bf16_t* Kb, int kpitch, const bf16_t* Vb, int vpitch,
;                                           int b, int ntiles, float kmax, f32x16 (&o)[DV / 32], float& linv) {
;     ...
;     for (int kt = 0; kt < ntiles; ++kt) {
;         if (kt + 1 < ntiles) gload(kt + 1);
;         const unsigned char* Ks = smem + (kt & 1) * BUF; const unsigned char* Vs = Ks + KBYTES;
;         const unsigned char* kp = Ks + r32 * KP + hi * 16;
;         bf16x8 pf[2][2];
; #pragma unroll
;         for (int kb = 0; kb < 2; ++kb) {
;             f32x16 s;
; #pragma unroll
;             for (int r = 0; r < 16; ++r) s[r] = nshift;
; #pragma unroll
;             for (int ds = 0; ds < 4; ++ds) {
;                 const bf16x8 kf = *(const bf16x8*)(kp + kb * 32 * KP + ds * 32);
;                 s = __builtin_amdgcn_mfma_f32_32x32x16_bf16(kf, qf[ds], s, 0, 0, 0);
;             }
;             float ls = 0.f;
; #pragma unroll
;             for (int r = 0; r < 16; ++r) { s[r] = __builtin_amdgcn_exp2f(s[r]); ls += s[r]; }
;             lsum += ls;
; #pragma unroll
;             for (int j = 0; j < 2; ++j) {
;                 u32x4 w0;
;                 w0.x = cvt_pk_bf16(s[8 * j + 0], s[8 * j + 1]); w0.y = cvt_pk_bf16(s[8 * j + 2], s[8 * j + 3]); w0.z = cvt_pk_bf16(s[8 * j + 4], s[8 * j + 5]); w0.w = cvt_pk_bf16(s[8 * j + 6], s[8 * j + 7]);
;                 pf[kb][j] = __builtin_bit_cast(bf16x8, w0);
;             }
;         }
;         const unsigned char* vp = Vs + (4 * hi + q4) * VP + (16 * nhalf + 4 * p4) * 2;
; #pragma unroll
;         for (int d0 = 0; d0 < DV / 32; ++d0) {
; #pragma unroll
;             for (int kb = 0; kb < 2; ++kb)
; #pragma unroll
;                 for (int j = 0; j < 2; ++j) {
;                     const unsigned char* a = vp + (32 * kb + 16 * j) * VP + d0 * 64;
;                     const s16x4 lo = ld_tr(a), h4 = ld_tr(a + 8 * VP);
;                     const bf16x8 vf = (bf16x8){lo[0], lo[1], lo[2], lo[3], h4[0], h4[1], h4[2], h4[3]};
;                     o[d0] = __builtin_amdgcn_mfma_f32_32x32x16_bf16(vf, pf[kb][j], o[d0], 0, 0, 0);
;                 }
;             if (d0 & 1) __builtin_amdgcn_sched_barrier(0);
;         }
;         if (kt + 1 < ntiles) lwrite((kt + 1) & 1);
;         __syncthreads();
	v_mfma_f32_32x32x16_bf16 v[16:31], v[158:161], v[180:183], v[16:31]
	ds_read_b64_tr_b16 v[158:159], v143 offset:19520
	ds_read_b64_tr_b16 v[160:161], v143 offset:22080
	v_exp_f32_e32 v126, v126
	v_add_f32_e32 v169, v169, v124
	v_exp_f32_e32 v127, v127
	s_waitcnt lgkmcnt(6)
	v_mfma_f32_32x32x16_bf16 v[48:63], v[162:165], v[180:183], v[48:63]
	ds_read_b64_tr_b16 v[162:163], v143 offset:19584
	ds_read_b64_tr_b16 v[164:165], v143 offset:22144
	v_add_f32_e32 v169, v169, v125
	v_cvt_pk_bf16_f32 v190, v124, v125
	v_add_f32_e32 v169, v169, v126
	v_add_f32_e32 v169, v169, v127
	v_cvt_pk_bf16_f32 v191, v126, v127
	s_waitcnt lgkmcnt(6)
	v_mfma_f32_32x32x16_bf16 v[64:79], v[230:233], v[180:183], v[64:79]
	ds_read_b64_tr_b16 v[230:231], v143 offset:19648
	ds_read_b64_tr_b16 v[232:233], v143 offset:22208
	v_mfma_f32_32x32x16_bf16 v[112:127], v[198:201], v[96:99], v[32:47]
	v_exp_f32_e32 v80, v80
	v_exp_f32_e32 v81, v81
	v_exp_f32_e32 v82, v82
	v_mfma_f32_32x32x16_bf16 v[112:127], v[202:205], v[100:103], v[112:127]
	v_add_f32_e32 v169, v169, v80
	v_exp_f32_e32 v83, v83
	v_add_f32_e32 v169, v169, v81
	v_cvt_pk_bf16_f32 v176, v80, v81
	v_mfma_f32_32x32x16_bf16 v[112:127], v[206:209], v[104:107], v[112:127]
	v_exp_f32_e32 v84, v84
	v_add_f32_e32 v169, v169, v82
	v_exp_f32_e32 v85, v85
	v_mfma_f32_32x32x16_bf16 v[112:127], v[150:153], v[108:111], v[112:127]
	v_add_f32_e32 v169, v169, v83
	v_cvt_pk_bf16_f32 v177, v82, v83
	v_exp_f32_e32 v86, v86
	v_add_f32_e32 v169, v169, v84
	s_waitcnt lgkmcnt(6)
	v_mfma_f32_32x32x16_bf16 v[0:15], v[154:157], v[184:187], v[0:15]
	ds_read_b64_tr_b16 v[154:155], v143 offset:24576
	ds_read_b64_tr_b16 v[156:157], v143 offset:27136
	v_exp_f32_e32 v87, v87
	v_add_f32_e32 v169, v169, v85
	v_cvt_pk_bf16_f32 v178, v84, v85
	v_exp_f32_e32 v88, v88
	s_waitcnt lgkmcnt(6)
	v_mfma_f32_32x32x16_bf16 v[16:31], v[158:161], v[184:187], v[16:31]
	ds_read_b64_tr_b16 v[158:159], v143 offset:24640
	ds_read_b64_tr_b16 v[160:161], v143 offset:27200
	v_add_f32_e32 v169, v169, v86
	v_exp_f32_e32 v89, v89
	v_add_f32_e32 v169, v169, v87
	s_waitcnt lgkmcnt(6)
	v_mfma_f32_32x32x16_bf16 v[48:63], v[162:165], v[184:187], v[48:63]
	ds_read_b64_tr_b16 v[162:163], v143 offset:24704
	ds_read_b64_tr_b16 v[164:165], v143 offset:27264
	v_cvt_pk_bf16_f32 v179, v86, v87
	v_exp_f32_e32 v90, v90
	v_add_f32_e32 v169, v169, v88
	v_exp_f32_e32 v91, v91
	s_waitcnt lgkmcnt(6)
	v_mfma_f32_32x32x16_bf16 v[64:79], v[230:233], v[184:187], v[64:79]
	ds_read_b64_tr_b16 v[230:231], v143 offset:24768
	ds_read_b64_tr_b16 v[232:233], v143 offset:27328
	v_add_f32_e32 v169, v169, v89
	v_cvt_pk_bf16_f32 v180, v88, v89
	v_exp_f32_e32 v92, v92
	s_waitcnt lgkmcnt(6)
	v_mfma_f32_32x32x16_bf16 v[0:15], v[154:157], v[188:191], v[0:15]
	ds_read_b64_tr_b16 v[154:155], v147 offset:9216
	ds_read_b64_tr_b16 v[156:157], v147 offset:11776
	v_add_f32_e32 v169, v169, v90
	v_exp_f32_e32 v93, v93
	v_add_f32_e32 v169, v169, v91
	v_cvt_pk_bf16_f32 v181, v90, v91
	s_waitcnt lgkmcnt(6)
	v_mfma_f32_32x32x16_bf16 v[16:31], v[158:161], v[188:191], v[16:31]
	ds_read_b64_tr_b16 v[158:159], v147 offset:9280
	ds_read_b64_tr_b16 v[160:161], v147 offset:11840
	v_add3_u32 v174, s57, v213, v138
	v_add3_u32 v175, s57, v141, v221
	v_add3_u32 v210, s58, v213, v138
	v_add3_u32 v211, s58, v141, v221
	v_exp_f32_e32 v94, v94
	v_add_f32_e32 v169, v169, v92
	v_exp_f32_e32 v95, v95
	s_waitcnt lgkmcnt(6)
	v_mfma_f32_32x32x16_bf16 v[48:63], v[162:165], v[188:191], v[48:63]
	ds_read_b64_tr_b16 v[162:163], v147 offset:9344
	ds_read_b64_tr_b16 v[164:165], v147 offset:11904
	s_mov_b32 s2, s56
	s_mov_b32 s56, s57
	s_mov_b32 s57, s58
	s_mov_b32 s58, s2
	s_add_i32 s59, s59, 1
	v_add_f32_e32 v169, v169, v93
	v_cvt_pk_bf16_f32 v182, v92, v93
	v_add_f32_e32 v169, v169, v94
	v_add_f32_e32 v169, v169, v95
	v_cvt_pk_bf16_f32 v183, v94, v95
	s_waitcnt lgkmcnt(6)
	v_mfma_f32_32x32x16_bf16 v[64:79], v[230:233], v[188:191], v[64:79]
	ds_read_b64_tr_b16 v[230:231], v147 offset:9408
	ds_read_b64_tr_b16 v[232:233], v147 offset:11968
	s_waitcnt lgkmcnt(0)
	s_barrier
; __device__ __forceinline__ float sum_x32(float v) { auto rr = __builtin_amdgcn_permlane32_swap(__float_as_uint(v), __float_as_uint(v), false, false); return __uint_as_float(rr[0]) + __uint_as_float(rr[1]); }
; __device__ __forceinline__ s16x4 ld_tr(const unsigned char* p) { return __builtin_bit_cast(s16x4, __builtin_amdgcn_ds_read_tr16_b64_v4i16((LAS s16x4*)p)); }
; template <int DV>
; __device__ __forceinline__ void attn_pass(const int tid, unsigned char* smem, const bf16_t* Q0, int qpitch, const bf16_t* Kb, int kpitch, const bf16_t* Vb, int vpitch,
;                                           int b, int ntiles, float kmax, f32x16 (&o)[DV / 32], float& linv) {
;     ...
;         const unsigned char* vp = Vs + (4 * hi + q4) * VP + (16 * nhalf + 4 * p4) * 2;
; #pragma unroll
;         for (int d0 = 0; d0 < DV / 32; ++d0) {
; #pragma unroll
;             for (int kb = 0; kb < 2; ++kb)
; #pragma unroll
;                 for (int j = 0; j < 2; ++j) {
;                     const unsigned char* a = vp + (32 * kb + 16 * j) * VP + d0 * 64;
;                     const s16x4 lo = ld_tr(a), h4 = ld_tr(a + 8 * VP);
;                     const bf16x8 vf = (bf16x8){lo[0], lo[1], lo[2], lo[3], h4[0], h4[1], h4[2], h4[3]};
;                     o[d0] = __builtin_amdgcn_mfma_f32_32x32x16_bf16(vf, pf[kb][j], o[d0], 0, 0, 0);
;                 }
;             if (d0 & 1) __builtin_amdgcn_sched_barrier(0);
;         }
;         if (kt + 1 < ntiles) lwrite((kt + 1) & 1);
;         __syncthreads();
;     }
;     lsum = sum_x32(lsum);
	v_mfma_f32_32x32x16_bf16 v[0:15], v[154:157], v[176:179], v[0:15]
	ds_read_b64_tr_b16 v[154:155], v175 offset:14336
	ds_read_b64_tr_b16 v[156:157], v175 offset:16896
	v_exp_f32_e32 v112, v112
	v_exp_f32_e32 v113, v113
	v_exp_f32_e32 v114, v114
	v_add_f32_e32 v169, v169, v112
	v_exp_f32_e32 v115, v115
	v_mfma_f32_32x32x16_bf16 v[16:31], v[158:161], v[176:179], v[16:31]
	ds_read_b64_tr_b16 v[158:159], v175 offset:14400
	ds_read_b64_tr_b16 v[160:161], v175 offset:16960
	v_add_f32_e32 v169, v169, v113
	v_cvt_pk_bf16_f32 v184, v112, v113
	v_exp_f32_e32 v116, v116
	v_add_f32_e32 v169, v169, v114
	v_exp_f32_e32 v117, v117
	v_mfma_f32_32x32x16_bf16 v[48:63], v[162:165], v[176:179], v[48:63]
	ds_read_b64_tr_b16 v[162:163], v175 offset:14464
	ds_read_b64_tr_b16 v[164:165], v175 offset:17024
	v_add_f32_e32 v169, v169, v115
	v_cvt_pk_bf16_f32 v185, v114, v115
	v_exp_f32_e32 v118, v118
	v_add_f32_e32 v169, v169, v116
	v_exp_f32_e32 v119, v119
	v_add_f32_e32 v169, v169, v117
	v_mfma_f32_32x32x16_bf16 v[64:79], v[230:233], v[176:179], v[64:79]
	ds_read_b64_tr_b16 v[230:231], v175 offset:14528
	ds_read_b64_tr_b16 v[232:233], v175 offset:17088
	v_cvt_pk_bf16_f32 v186, v116, v117
	v_exp_f32_e32 v120, v120
	v_add_f32_e32 v169, v169, v118
	v_exp_f32_e32 v121, v121
	v_add_f32_e32 v169, v169, v119
	v_cvt_pk_bf16_f32 v187, v118, v119
	s_waitcnt lgkmcnt(6)
	v_mfma_f32_32x32x16_bf16 v[0:15], v[154:157], v[180:183], v[0:15]
	ds_read_b64_tr_b16 v[154:155], v175 offset:19456
	ds_read_b64_tr_b16 v[156:157], v175 offset:22016
	v_exp_f32_e32 v122, v122
	v_add_f32_e32 v169, v169, v120
	v_exp_f32_e32 v123, v123
	v_add_f32_e32 v169, v169, v121
	v_cvt_pk_bf16_f32 v188, v120, v121
	v_exp_f32_e32 v124, v124
	s_waitcnt lgkmcnt(6)
	v_mfma_f32_32x32x16_bf16 v[16:31], v[158:161], v[180:183], v[16:31]
	ds_read_b64_tr_b16 v[158:159], v175 offset:19520
	ds_read_b64_tr_b16 v[160:161], v175 offset:22080
	v_add_f32_e32 v169, v169, v122
	v_exp_f32_e32 v125, v125
	v_add_f32_e32 v169, v169, v123
	v_cvt_pk_bf16_f32 v189, v122, v123
	v_exp_f32_e32 v126, v126
	s_waitcnt lgkmcnt(6)
	v_mfma_f32_32x32x16_bf16 v[48:63], v[162:165], v[180:183], v[48:63]
	ds_read_b64_tr_b16 v[162:163], v175 offset:19584
	ds_read_b64_tr_b16 v[164:165], v175 offset:22144
	v_add_f32_e32 v169, v169, v124
	v_exp_f32_e32 v127, v127
	v_add_f32_e32 v169, v169, v125
	v_cvt_pk_bf16_f32 v190, v124, v125
	v_add_f32_e32 v169, v169, v126
	v_add_f32_e32 v169, v169, v127
	v_cvt_pk_bf16_f32 v191, v126, v127
	s_waitcnt lgkmcnt(6)
	v_mfma_f32_32x32x16_bf16 v[64:79], v[230:233], v[180:183], v[64:79]
	ds_read_b64_tr_b16 v[230:231], v175 offset:19648
	ds_read_b64_tr_b16 v[232:233], v175 offset:22208
	s_waitcnt lgkmcnt(6)
	v_mfma_f32_32x32x16_bf16 v[0:15], v[154:157], v[184:187], v[0:15]
	ds_read_b64_tr_b16 v[154:155], v175 offset:24576
	ds_read_b64_tr_b16 v[156:157], v175 offset:27136
	s_waitcnt lgkmcnt(6)
	v_mfma_f32_32x32x16_bf16 v[16:31], v[158:161], v[184:187], v[16:31]
	ds_read_b64_tr_b16 v[158:159], v175 offset:24640
	ds_read_b64_tr_b16 v[160:161], v175 offset:27200
	s_waitcnt lgkmcnt(6)
	v_mfma_f32_32x32x16_bf16 v[48:63], v[162:165], v[184:187], v[48:63]
	ds_read_b64_tr_b16 v[162:163], v175 offset:24704
	ds_read_b64_tr_b16 v[164:165], v175 offset:27264
	s_waitcnt lgkmcnt(6)
	v_mfma_f32_32x32x16_bf16 v[64:79], v[230:233], v[184:187], v[64:79]
	ds_read_b64_tr_b16 v[230:231], v175 offset:24768
	ds_read_b64_tr_b16 v[232:233], v175 offset:27328
	s_waitcnt lgkmcnt(6)
	v_mfma_f32_32x32x16_bf16 v[0:15], v[154:157], v[188:191], v[0:15]
	s_waitcnt lgkmcnt(4)
	v_mfma_f32_32x32x16_bf16 v[16:31], v[158:161], v[188:191], v[16:31]
	s_waitcnt lgkmcnt(2)
	v_mfma_f32_32x32x16_bf16 v[48:63], v[162:165], v[188:191], v[48:63]
	s_waitcnt lgkmcnt(0)
	v_mfma_f32_32x32x16_bf16 v[64:79], v[230:233], v[188:191], v[64:79]
	s_waitcnt lgkmcnt(0)
	s_barrier
	s_waitcnt vmcnt(0)
